# v29 plus MLA loop K/V tile loads addressed by running SGPR bases (no per-tile 64-bit VALU address math)
# speedup vs baseline: 1.0143x; 1.0008x over previous
; __device__ __forceinline__ float bflo(unsigned w) { return __uint_as_float(w << 16); }
;     constexpr int ND = (MODE == 2) ? 6 : 4, QP = 1536;
;     const int r32 = lane & 31, hi = lane >> 5;
; #pragma unroll
;     for (int qb = 0; qb < 2; ++qb) {
;         __builtin_amdgcn_sched_barrier(0);
;         const bf16_t* src = U.q + (size_t)(32 * qb + r32) * QP + 8 * hi;
;         u32x4 raw[ND];
; #pragma unroll
;         for (int d0 = 0; d0 < ND; ++d0) raw[d0] = *(const u32x4*)(src + 16 * d0);
;         int pos = U.tq0 + 32 * qb + r32; asm volatile("" : "+v"(pos));
;         if constexpr (MODE == 1) {
; #pragma unroll
;             for (int d0 = 0; d0 < ND; ++d0) qf[qb][d0] = __builtin_bit_cast(bf16x8, raw[d0]);
;         } else if constexpr (MODE == 0) {
;             float v[4][8]; float ss = 0.f;
; #pragma unroll
;             for (int d0 = 0; d0 < 4; ++d0)
; #pragma unroll
;                 for (int j = 0; j < 4; ++j) { const unsigned w = raw[d0][j]; v[d0][2 * j] = bflo(w); v[d0][2 * j + 1] = bfhi(w); ss += v[d0][2 * j] * v[d0][2 * j] + v[d0][2 * j + 1] * v[d0][2 * j + 1]; }
;             ss = pairsum(ss);
;             const float rstd = rsqrtf(ss * (1.0f / 64.0f) + EPSN) * C2_64;
; #pragma unroll
;             for (int d0 = 0; d0 < 4; ++d0)
; #pragma unroll
;                 for (int j = 0; j < 8; ++j) v[d0][j] *= rstd * U.gain[16 * d0 + 8 * hi + j];
;             const int row = pos >> 6, col = pos & 63;
; #pragma unroll
;             for (int j = 0; j < 8; ++j) {
;                 __builtin_amdgcn_sched_barrier(0);
;                 const float fi = hi ? invf_c(8 + j) : invf_c(j); float c, s;
;                 rope_cs(row, fi, c, s); { const float x1 = v[0][j], x2 = v[1][j]; v[0][j] = x1 * c - x2 * s; v[1][j] = x2 * c + x1 * s; }
;                 rope_cs(col, fi, c, s); { const float x1 = v[2][j], x2 = v[3][j]; v[2][j] = x1 * c - x2 * s; v[3][j] = x2 * c + x1 * s; }
;             }
; #pragma unroll
;             for (int d0 = 0; d0 < 4; ++d0) { u32x4 w; w.x = pk(v[d0][0], v[d0][1]); w.y = pk(v[d0][2], v[d0][3]); w.z = pk(v[d0][4], v[d0][5]); w.w = pk(v[d0][6], v[d0][7]); qf[qb][d0] = __builtin_bit_cast(bf16x8, w); }
;         } else {
; #pragma unroll
;             for (int d0 = 0; d0 < 4; ++d0) qf[qb][d0] = __builtin_bit_cast(bf16x8, raw[d0]);
;             float a[8], b[8];
; #pragma unroll
.LBB0_922:
	s_lshr_b64 s[6:7], s[20:21], 4
	s_lshl_b64 s[8:9], s[6:7], 25
	s_add_u32 s40, s18, s8
	s_addc_u32 s41, s19, s9
	s_add_i32 s9, s59, s50
	s_and_b32 s44, s58, 15
	s_lshr_b32 s8, s9, 4
	s_and_b32 s24, s9, 15
	s_mov_b32 s9, s31
	s_lshl_b32 s30, s44, 13
	s_lshl_b64 s[6:7], s[6:7], 20
	s_lshl_b64 s[10:11], s[8:9], 14
	s_add_u32 s22, s10, s63
	s_addc_u32 s23, s11, s66
	s_mul_i32 s10, s23, 0xc00
	s_mul_hi_u32 s11, s22, 0xc00
	s_add_i32 s11, s11, s10
	s_mul_i32 s10, s22, 0xc00
	s_add_u32 s10, s26, s10
	s_addc_u32 s11, s27, s11
	s_mul_i32 s12, s24, 0xc0
	s_add_u32 s42, s10, s12
	s_addc_u32 s43, s11, 0
	s_lshl_b64 s[12:13], s[8:9], 25
	s_add_u32 s10, s33, s12
	s_addc_u32 s11, s37, s13
	s_lshl_b32 s60, s24, 6
	s_lshl_b32 s35, s24, 7
	s_add_u32 s10, s10, s35
	s_addc_u32 s11, s11, 0
	s_lshl_b64 s[8:9], s[8:9], 20
	s_add_u32 s8, s25, s8
	s_addc_u32 s9, s52, s9
	s_add_u32 s12, s46, s12
	s_addc_u32 s13, s47, s13
	s_lshl_b32 s24, s24, 13
	s_add_u32 s12, s12, s24
	v_mbcnt_lo_u32_b32 v8, -1, 0
	v_mbcnt_hi_u32_b32 v8, -1, v8
	s_addc_u32 s13, s13, 0
	v_and_b32_e32 v237, 63, v8
	v_and_b32_e32 v187, 31, v8
	v_cmp_gt_u32_e32 vcc, 32, v237
	v_mul_u32_u24_e32 v0, 0x600, v187
	v_lshlrev_b32_e32 v96, 1, v0
	v_lshrrev_b32_e32 v2, 1, v8
	v_lshl_add_u64 v[0:1], s[42:43], 0, v[96:97]
	v_and_b32_e32 v96, 16, v2
	v_lshl_add_u64 v[10:11], v[0:1], 0, v[96:97]
	global_load_dwordx4 v[0:3], v[10:11], off offset:128
	global_load_dwordx4 v[4:7], v[10:11], off offset:160
	global_load_dwordx4 v[98:101], v[10:11], off
	global_load_dwordx4 v[102:105], v[10:11], off offset:32
	global_load_dwordx4 v[106:109], v[10:11], off offset:64
	global_load_dwordx4 v[110:113], v[10:11], off offset:96
	v_or_b32_e32 v9, s63, v187
	s_waitcnt vmcnt(5)
	v_and_b32_e32 v18, 0xffff0000, v0
	v_cvt_f32_i32_e32 v9, v9
	s_waitcnt vmcnt(4)
	v_and_b32_e32 v19, 0xffff0000, v4
	v_and_b32_e32 v20, 0xffff0000, v1
	v_and_b32_e32 v21, 0xffff0000, v5
	v_and_b32_e32 v22, 0xffff0000, v2
	v_and_b32_e32 v23, 0xffff0000, v6
	v_and_b32_e32 v24, 0xffff0000, v3
	v_and_b32_e32 v25, 0xffff0000, v7
	v_mov_b32_e32 v10, 0x3c23d70a
	v_cndmask_b32_e64 v27, v10, 1.0, vcc
	v_mul_f32_e32 v10, v27, v9
	v_mul_f32_e32 v11, 0.15915494, v10
	v_rndne_f32_e32 v11, v11
	v_fmac_f32_e32 v10, 0xc0c90fdb, v11
	v_fmac_f32_e32 v10, 0x343bbd2e, v11
	v_mul_f32_e32 v11, 0.15915494, v10
	v_sin_f32_e32 v10, v11
	v_cos_f32_e32 v11, v11
	v_lshlrev_b32_e32 v13, 16, v0
	v_lshlrev_b32_e32 v12, 16, v4
	v_mov_b32_e32 v17, v10
	v_mov_b32_e32 v16, v11
	v_pk_mul_f32 v[14:15], v[10:11], v[12:13]
	v_pk_mul_f32 v[10:11], v[16:17], v[12:13]
	v_mov_b32_e32 v0, 0x3bb8449c
	v_mov_b32_e32 v4, 0x3f0ff59a
	v_cndmask_b32_e32 v29, v0, v4, vcc
	v_mul_f32_e32 v0, v29, v9
	v_mul_f32_e32 v4, 0.15915494, v0
	v_rndne_f32_e32 v4, v4
	v_fmac_f32_e32 v0, 0xc0c90fdb, v4
	v_fmac_f32_e32 v0, 0x343bbd2e, v4
	v_mul_f32_e32 v0, 0.15915494, v0
	v_cos_f32_e32 v4, v0
	v_sin_f32_e32 v0, v0
	v_mov_b32_e32 v12, v15
	v_mov_b32_e32 v16, v11
	v_mul_f32_e32 v13, v4, v18
	v_mul_f32_e32 v15, v0, v19
	v_pk_add_f32 v[12:13], v[12:13], v[14:15] neg_lo:[0,1] neg_hi:[0,1]
	v_mul_f32_e32 v15, v4, v19
	v_mul_f32_e32 v17, v0, v18
	v_mov_b32_e32 v14, v10
	v_pk_add_f32 v[10:11], v[14:15], v[16:17]
	v_mov_b32_e32 v0, 0x3b4f3e37
	v_mov_b32_e32 v4, 0x3ea1e89b
	v_cndmask_b32_e32 v47, v0, v4, vcc
	v_mul_f32_e32 v0, v47, v9
	v_mul_f32_e32 v4, 0.15915494, v0
	v_rndne_f32_e32 v4, v4
	v_fmac_f32_e32 v0, 0xc0c90fdb, v4
	v_fmac_f32_e32 v0, 0x343bbd2e, v4
	v_mul_f32_e32 v0, 0.15915494, v0
	v_sin_f32_e32 v14, v0
	v_cos_f32_e32 v15, v0
	v_lshlrev_b32_e32 v1, 16, v1
	v_lshlrev_b32_e32 v0, 16, v5
	v_mov_b32_e32 v17, v14
	v_mov_b32_e32 v16, v15
	v_pk_mul_f32 v[4:5], v[14:15], v[0:1]
	v_pk_mul_f32 v[0:1], v[16:17], v[0:1]
	v_mov_b32_e32 v14, 0x3ae91528
	v_mov_b32_e32 v15, 0x3e361887
	v_cndmask_b32_e32 v53, v14, v15, vcc
	v_mul_f32_e32 v14, v53, v9
	v_mul_f32_e32 v15, 0.15915494, v14
	v_rndne_f32_e32 v15, v15
	v_fmac_f32_e32 v14, 0xc0c90fdb, v15
	v_fmac_f32_e32 v14, 0x343bbd2e, v15
	v_mul_f32_e32 v14, 0.15915494, v14
	v_cos_f32_e32 v16, v14
	v_sin_f32_e32 v17, v14
	v_mov_b32_e32 v14, v5
	v_mul_f32_e32 v15, v16, v20
	v_mul_f32_e32 v5, v17, v21
	v_pk_add_f32 v[4:5], v[14:15], v[4:5] neg_lo:[0,1] neg_hi:[0,1]
	v_mul_f32_e32 v15, v16, v21
	v_mul_f32_e32 v17, v17, v20
	v_mov_b32_e32 v14, v0
	v_mov_b32_e32 v16, v1
	v_pk_add_f32 v[0:1], v[14:15], v[16:17]
	v_mov_b32_e32 v14, 0x3a83126f
	v_mov_b32_e32 v15, 0x3dcccccd
	v_cndmask_b32_e32 v56, v14, v15, vcc
	v_mul_f32_e32 v14, v56, v9
	v_mul_f32_e32 v15, 0.15915494, v14
	v_rndne_f32_e32 v15, v15
	v_fmac_f32_e32 v14, 0xc0c90fdb, v15
	v_fmac_f32_e32 v14, 0x343bbd2e, v15
	v_mul_f32_e32 v15, 0.15915494, v14
	v_sin_f32_e32 v14, v15
	v_cos_f32_e32 v15, v15
	v_lshlrev_b32_e32 v17, 16, v2
	v_lshlrev_b32_e32 v16, 16, v6
	v_mov_b32_e32 v21, v14
	v_mov_b32_e32 v20, v15
	v_pk_mul_f32 v[18:19], v[14:15], v[16:17]
	v_pk_mul_f32 v[14:15], v[20:21], v[16:17]
	v_mov_b32_e32 v2, 0x3d6655c3
	v_cndmask_b32_e32 v57, v193, v2, vcc
	v_mul_f32_e32 v2, v57, v9
	v_mul_f32_e32 v6, 0.15915494, v2
	v_rndne_f32_e32 v6, v6
	v_fmac_f32_e32 v2, 0xc0c90fdb, v6
	v_fmac_f32_e32 v2, 0x343bbd2e, v6
	v_mul_f32_e32 v2, 0.15915494, v2
	v_cos_f32_e32 v6, v2
	v_sin_f32_e32 v2, v2
	v_mov_b32_e32 v16, v19
	v_mov_b32_e32 v20, v15
	v_mul_f32_e32 v17, v6, v22
	v_mul_f32_e32 v19, v2, v23
	v_pk_add_f32 v[16:17], v[16:17], v[18:19] neg_lo:[0,1] neg_hi:[0,1]
	v_mul_f32_e32 v19, v6, v23
	v_mul_f32_e32 v21, v2, v22
	v_mov_b32_e32 v18, v14
	v_pk_add_f32 v[14:15], v[18:19], v[20:21]
	v_mov_b32_e32 v2, 0x39a5cb5f
	v_mov_b32_e32 v6, 0x3d0186e2
	v_cndmask_b32_e32 v22, v2, v6, vcc
	v_mul_f32_e32 v2, v22, v9
	v_mul_f32_e32 v6, 0.15915494, v2
; __device__ __forceinline__ float bflo(unsigned w) { return __uint_as_float(w << 16); }
; __device__ __forceinline__ float bfhi(unsigned w) { return __uint_as_float(w & 0xffff0000u); }
; __device__ __forceinline__ unsigned pk(float lo, float hi) { f32x2_t v = {lo, hi}; bf16x2_t b = __builtin_convertvector(v, bf16x2_t); return __builtin_bit_cast(unsigned, b); }
; #define BAR_LDS() asm volatile("s_waitcnt lgkmcnt(0)\n\ts_barrier" ::: "memory")
; #define ATT_LOADS(RK, RR, RV, tt) do { RK = *(const u32x4*)((const char*)(U.k + (size_t)(tt) * 64 * KP) + kgo); if (MODE == 2) RR = *(const u32x2*)((const char*)(U.kr + (size_t)(tt) * 64 * 32) + krgo); \
;         RV = *(const u32x4*)((const char*)(U.vt + (size_t)(tt) * VTS) + vgo); } while (0)
; #define ATT_LOAD(tt) ATT_LOADS(rk, rr, rv, tt)
; #define ATT_STORE(ss) ATT_STORES(rk, rr, rv, ss)
;     ...
;             for (int j = 0; j < 4; ++j) { a[2 * j] = bflo(raw[ND - 2][j]); a[2 * j + 1] = bfhi(raw[ND - 2][j]); b[2 * j] = bflo(raw[ND - 1][j]); b[2 * j + 1] = bfhi(raw[ND - 1][j]); }
; #pragma unroll
;             for (int j = 0; j < 8; ++j) { __builtin_amdgcn_sched_barrier(0); const float fi = hi ? invf_c(8 + j) : invf_c(j); float c, s; rope_cs(pos, fi, c, s);
;                 const float x1 = a[j], x2 = b[j]; a[j] = x1 * c - x2 * s; b[j] = x2 * c + x1 * s; }
;             u32x4 wa, wb; wa.x = pk(a[0], a[1]); wa.y = pk(a[2], a[3]); wa.z = pk(a[4], a[5]); wa.w = pk(a[6], a[7]); wb.x = pk(b[0], b[1]); wb.y = pk(b[2], b[3]); wb.z = pk(b[4], b[5]); wb.w = pk(b[6], b[7]);
;             qf[qb][ND - 2] = __builtin_bit_cast(bf16x8, wa); qf[qb][ND - 1] = __builtin_bit_cast(bf16x8, wb);
; template <int MODE, bool FAST> __device__ __forceinline__ bool attn_unit(LAS unsigned char* lds, const AttU& U, const int wv) {
;     ...
;     const int NT = U.kt1 - U.kt0;
;     ATT_LOAD(U.kt0); ATT_STORE(0);
;     if (NT > 1) { ATT_LOAD(U.kt0 + 1); ATT_STORE(1); }
;     if (NT > 2) ATT_LOAD(U.kt0 + 2);
;     if constexpr (FAST) { if (NT > 3) ATT_LOADS(rk2, rr2, rv2, U.kt0 + 3); }
;     BAR_LDS();
	v_rndne_f32_e32 v6, v6
	v_fmac_f32_e32 v2, 0xc0c90fdb, v6
	v_fmac_f32_e32 v2, 0x343bbd2e, v6
	v_mul_f32_e32 v2, 0.15915494, v2
	v_sin_f32_e32 v18, v2
	v_cos_f32_e32 v19, v2
	v_lshlrev_b32_e32 v3, 16, v3
	v_lshlrev_b32_e32 v2, 16, v7
	v_mov_b32_e32 v21, v18
	v_mov_b32_e32 v20, v19
	v_pk_mul_f32 v[6:7], v[18:19], v[2:3]
	v_pk_mul_f32 v[2:3], v[20:21], v[2:3]
	v_cndmask_b32_e32 v86, v234, v235, vcc
	v_mul_f32_e32 v9, v86, v9
	v_mul_f32_e32 v18, 0.15915494, v9
	v_rndne_f32_e32 v18, v18
	v_fmac_f32_e32 v9, 0xc0c90fdb, v18
	v_fmac_f32_e32 v9, 0x343bbd2e, v18
	v_mul_f32_e32 v9, 0.15915494, v9
	v_cos_f32_e32 v20, v9
	v_sin_f32_e32 v9, v9
	v_mov_b32_e32 v18, v7
	v_cvt_pk_bf16_f32 v114, v12, v13
	v_mul_f32_e32 v19, v20, v24
	v_mul_f32_e32 v7, v9, v25
	v_pk_add_f32 v[6:7], v[18:19], v[6:7] neg_lo:[0,1] neg_hi:[0,1]
	v_mul_f32_e32 v19, v20, v25
	v_mul_f32_e32 v21, v9, v24
	v_mov_b32_e32 v18, v2
	v_mov_b32_e32 v20, v3
	v_pk_add_f32 v[2:3], v[18:19], v[20:21]
	v_cvt_pk_bf16_f32 v115, v4, v5
	v_cvt_pk_bf16_f32 v116, v16, v17
	v_cvt_pk_bf16_f32 v117, v6, v7
	v_cvt_pk_bf16_f32 v118, v10, v11
	v_cvt_pk_bf16_f32 v119, v0, v1
	v_cvt_pk_bf16_f32 v120, v14, v15
	v_cvt_pk_bf16_f32 v121, v2, v3
	v_or_b32_e32 v9, 32, v237
	v_mul_u32_u24_e32 v0, 0x600, v9
	v_lshlrev_b32_e32 v0, 1, v0
	v_mov_b32_e32 v1, v97
	v_lshl_add_u64 v[0:1], s[42:43], 0, v[0:1]
	v_lshl_add_u64 v[4:5], v[0:1], 0, v[96:97]
	global_load_dwordx4 v[122:125], v[4:5], off
	global_load_dwordx4 v[126:129], v[4:5], off offset:32
	global_load_dwordx4 v[130:133], v[4:5], off offset:64
	global_load_dwordx4 v[134:137], v[4:5], off offset:96
	global_load_dwordx4 v[0:3], v[4:5], off offset:128
	s_nop 0
	global_load_dwordx4 v[4:7], v[4:5], off offset:160
	v_or_b32_e32 v9, s63, v9
	s_nop 0
	v_cvt_f32_i32_e32 v87, v9
	v_add_u32_e32 v9, s36, v8
	v_and_b32_e32 v10, 7, v8
	v_ashrrev_i32_e32 v88, 3, v9
	v_lshlrev_b32_e32 v28, 4, v10
	v_mul_f32_e32 v11, v22, v87
	v_lshl_or_b32 v96, v88, 11, v28
	v_mul_f32_e32 v12, 0.15915494, v11
	v_lshlrev_b32_e32 v89, 3, v10
	v_lshlrev_b32_e32 v66, 6, v88
	v_lshl_add_u64 v[34:35], s[10:11], 0, v[96:97]
	v_rndne_f32_e32 v12, v12
	v_or_b32_e32 v30, v66, v89
	v_mov_b32_e32 v31, v97
	v_add_co_u32_e32 v18, vcc, s39, v34
	v_fmac_f32_e32 v11, 0xc0c90fdb, v12
	v_lshl_add_u64 v[36:37], s[8:9], 0, v[30:31]
	v_addc_co_u32_e32 v19, vcc, 0, v35, vcc
	v_fmac_f32_e32 v11, 0x343bbd2e, v12
	v_lshlrev_b32_e32 v32, 4, v9
	v_mov_b32_e32 v33, v97
	v_add_co_u32_e32 v40, vcc, s92, v36
	v_mul_f32_e32 v46, 0.15915494, v11
	global_load_dwordx4 v[10:13], v96, s[10:11]
	global_load_dwordx4 v[14:17], v32, s[12:13]
	v_lshl_add_u64 v[38:39], s[12:13], 0, v[32:33]
	global_load_dwordx4 v[18:21], v[18:19], off
	v_addc_co_u32_e32 v41, vcc, 0, v37, vcc
	global_load_dwordx2 v[42:43], v30, s[8:9]
	global_load_dwordx2 v[44:45], v[40:41], off offset:-4096
	v_add_co_u32_e32 v22, vcc, s39, v38
	v_mul_f32_e32 v9, v27, v87
	s_nop 0
	v_addc_co_u32_e32 v23, vcc, 0, v39, vcc
	global_load_dwordx4 v[22:25], v[22:23], off
	v_mul_f32_e32 v27, 0.15915494, v9
	v_rndne_f32_e32 v27, v27
	v_fmac_f32_e32 v9, 0xc0c90fdb, v27
	v_fmac_f32_e32 v9, 0x343bbd2e, v27
	v_mul_f32_e32 v9, 0.15915494, v9
	v_cos_f32_e32 v48, v9
	v_sin_f32_e32 v50, v9
	v_mul_f32_e32 v9, v29, v87
	v_mul_f32_e32 v27, 0.15915494, v9
	v_rndne_f32_e32 v27, v27
	v_fmac_f32_e32 v9, 0xc0c90fdb, v27
	v_fmac_f32_e32 v9, 0x343bbd2e, v27
	v_mul_f32_e32 v9, 0.15915494, v9
	v_cos_f32_e32 v49, v9
	v_sin_f32_e32 v51, v9
	v_mul_f32_e32 v9, v47, v87
	v_mul_f32_e32 v27, 0.15915494, v9
	v_rndne_f32_e32 v27, v27
	v_fmac_f32_e32 v9, 0xc0c90fdb, v27
	v_fmac_f32_e32 v9, 0x343bbd2e, v27
	v_mul_f32_e32 v9, 0.15915494, v9
	v_cos_f32_e32 v52, v9
	v_sin_f32_e32 v54, v9
	v_mul_f32_e32 v9, v53, v87
	v_mul_f32_e32 v27, 0.15915494, v9
	v_rndne_f32_e32 v27, v27
	v_fmac_f32_e32 v9, 0xc0c90fdb, v27
	v_fmac_f32_e32 v9, 0x343bbd2e, v27
	v_mul_f32_e32 v9, 0.15915494, v9
	v_cos_f32_e32 v53, v9
	v_sin_f32_e32 v55, v9
	v_mul_f32_e32 v9, v56, v87
	v_mul_f32_e32 v27, 0.15915494, v9
	v_rndne_f32_e32 v27, v27
	v_fmac_f32_e32 v9, 0xc0c90fdb, v27
	v_fmac_f32_e32 v9, 0x343bbd2e, v27
	v_mul_f32_e32 v9, 0.15915494, v9
	v_cos_f32_e32 v56, v9
	v_sin_f32_e32 v58, v9
	v_mul_f32_e32 v9, v57, v87
	v_mul_f32_e32 v27, 0.15915494, v9
	v_rndne_f32_e32 v27, v27
	v_fmac_f32_e32 v9, 0xc0c90fdb, v27
	v_fmac_f32_e32 v9, 0x343bbd2e, v27
	v_mul_lo_u32 v29, v88, s5
	s_mov_b32 s8, 0x60000
	v_mul_f32_e32 v9, 0.15915494, v9
	v_bfe_u32 v27, v8, 5, 1
	v_add_u32_e32 v238, v29, v28
	v_add_co_u32_e32 v8, vcc, s8, v38
	v_cos_f32_e32 v57, v9
	v_sin_f32_e32 v59, v9
	v_addc_co_u32_e32 v9, vcc, 0, v39, vcc
	v_sub_u32_e32 v239, v238, v89
	v_sub_u32_e32 v240, v238, v66
	v_add_u32_e32 v47, 0, v238
	global_load_dwordx4 v[138:141], v[8:9], off
	v_add_u32_e32 v8, 0, v239
	v_add_u32_e32 v9, 0, v240
	global_load_dwordx2 v[188:189], v[40:41], off
	v_lshlrev_b32_e32 v186, 4, v27
	v_mad_u32_u24 v241, v187, s5, v186
	v_add_u32_e32 v242, 0, v241
	s_waitcnt vmcnt(9)
	v_lshlrev_b32_e32 v62, 16, v0
	v_and_b32_e32 v63, 0xffff0000, v0
	s_waitcnt vmcnt(7)
	ds_write_b128 v47, v[10:13]
	v_lshlrev_b32_e32 v60, 16, v4
	v_and_b32_e32 v61, 0xffff0000, v4
	v_pk_mul_f32 v[64:65], v[50:51], v[62:63]
	v_lshlrev_b32_e32 v0, 16, v1
	s_waitcnt vmcnt(4)
	ds_write_b64 v8, v[42:43] offset:128
	ds_write_b128 v9, v[14:17] offset:13312
	ds_write_b128 v47, v[18:21] offset:22528
	s_waitcnt vmcnt(3)
	ds_write_b64 v8, v[44:45] offset:22656
	s_waitcnt vmcnt(2)
	ds_write_b128 v9, v[22:25] offset:35840
	v_add_co_u32_e32 v8, vcc, s4, v34
	v_pk_fma_f32 v[84:85], v[48:49], v[60:61], v[64:65]
	s_nop 0
	v_addc_co_u32_e32 v9, vcc, 0, v35, vcc
	v_add_co_u32_e32 v10, vcc, s4, v38
	v_and_b32_e32 v1, 0xffff0000, v1
	s_nop 0
	v_addc_co_u32_e32 v11, vcc, 0, v39, vcc
	global_load_dwordx4 v[142:145], v[8:9], off
	global_load_dwordx4 v[146:149], v[10:11], off
	v_add_co_u32_e32 v8, vcc, s8, v34
	s_movk_i32 s8, 0x3000
	s_nop 0
	v_addc_co_u32_e32 v9, vcc, 0, v35, vcc
	global_load_dwordx4 v[150:153], v[8:9], off
	v_add_co_u32_e32 v8, vcc, s8, v36
	v_lshlrev_b32_e32 v4, 16, v5
	s_nop 0
	v_addc_co_u32_e32 v9, vcc, 0, v37, vcc
	global_load_dwordx2 v[190:191], v[8:9], off
	s_waitcnt lgkmcnt(0)
	s_barrier
; #define LAS __attribute__((address_space(3)))
; template <int MODE, bool FAST> __device__ __forceinline__ bool attn_unit(LAS unsigned char* lds, const AttU& U, const int wv) {
;     ...
;     pb[1][0] = (bf16x8){0, 0, 0, 0, 0, 0, 0, 0}; pb[1][1] = pb[1][0];
;     ATT_QK(0, 0, 0);
;     bf16x8 kpre[NPRE > 0 ? NPRE : 1];
; #pragma unroll
;     for (int i_ = 0; i_ < NPRE; ++i_) kpre[i_] = *(LAS const bf16x8*)(lds + koff + i_ * 32);
	ds_read_b128 v[80:83], v242
	ds_read_b128 v[174:177], v242 offset:32
	s_waitcnt lgkmcnt(1)
	v_mfma_f32_32x32x16_bf16 v[64:79], v[80:83], v[98:101], 0
	ds_read_b128 v[170:173], v242 offset:64
	v_and_b32_e32 v5, 0xffff0000, v5
	v_mul_f32_e64 v8, v54, v0
	v_mul_f32_e64 v9, v55, v1
	v_lshlrev_b32_e32 v18, 16, v3
	v_pk_fma_f32 v[12:13], v[52:53], v[4:5], v[8:9]
	v_pk_mul_f32 v[4:5], v[54:55], v[4:5]
	v_lshlrev_b32_e32 v8, 16, v2
	s_waitcnt lgkmcnt(1)
	v_mfma_f32_32x32x16_bf16 v[64:79], v[174:177], v[102:105], v[64:79]
	v_and_b32_e32 v9, 0xffff0000, v2
	v_fma_f32 v4, v52, v0, -v4
	v_fma_f32 v5, v53, v1, -v5
	v_lshlrev_b32_e32 v0, 16, v6
	v_and_b32_e32 v1, 0xffff0000, v6
	v_pk_mul_f32 v[10:11], v[58:59], v[8:9]
	v_and_b32_e32 v19, 0xffff0000, v3
	v_pk_fma_f32 v[14:15], v[56:57], v[0:1], v[10:11]
	v_pk_mul_f32 v[0:1], v[58:59], v[0:1]
	v_cos_f32_e32 v26, v46
	v_pk_fma_f32 v[16:17], v[56:57], v[8:9], v[0:1] neg_lo:[0,0,1] neg_hi:[0,0,1]
	ds_read_b128 v[8:11], v242 offset:96
	s_waitcnt lgkmcnt(1)
	v_mfma_f32_32x32x16_bf16 v[64:79], v[170:173], v[106:109], v[64:79]
	v_mul_f32_e32 v0, v86, v87
	v_mul_f32_e32 v1, 0.15915494, v0
	v_rndne_f32_e32 v1, v1
	v_fmac_f32_e32 v0, 0xc0c90fdb, v1
	v_fmac_f32_e32 v0, 0x343bbd2e, v1
	v_mul_f32_e32 v0, 0.15915494, v0
	v_sin_f32_e32 v47, v0
	v_cos_f32_e32 v27, v0
	ds_read_b128 v[0:3], v242 offset:128
	s_waitcnt lgkmcnt(1)
	v_mfma_f32_32x32x16_bf16 v[64:79], v[8:11], v[110:113], v[64:79]
	v_sin_f32_e32 v46, v46
	v_lshlrev_b32_e32 v6, 16, v7
	v_and_b32_e32 v7, 0xffff0000, v7
	v_cvt_pk_bf16_f32 v155, v4, v5
	v_pk_mul_f32 v[8:9], v[46:47], v[18:19]
	v_pk_mul_f32 v[50:51], v[50:51], v[60:61]
	v_pk_fma_f32 v[8:9], v[26:27], v[6:7], v[8:9]
	v_pk_mul_f32 v[6:7], v[46:47], v[6:7]
	v_pk_fma_f32 v[48:49], v[48:49], v[62:63], v[50:51] neg_lo:[0,0,1] neg_hi:[0,0,1]
	v_pk_fma_f32 v[10:11], v[26:27], v[18:19], v[6:7] neg_lo:[0,0,1] neg_hi:[0,0,1]
	ds_read_b128 v[4:7], v242 offset:160
	s_waitcnt lgkmcnt(1)
	v_mfma_f32_32x32x16_bf16 v[64:79], v[0:3], v[114:117], v[64:79]
	v_lshlrev_b32_e32 v0, 6, v187
	s_add_u32 s6, s56, s6
	v_cvt_pk_bf16_f32 v154, v48, v49
	v_sub_u32_e32 v243, v241, v0
	s_addc_u32 s7, s57, s7
	v_mov_b32_e32 v48, 0
	v_cvt_pk_bf16_f32 v156, v16, v17
	s_waitcnt lgkmcnt(0)
	v_mfma_f32_32x32x16_bf16 v[64:79], v[4:7], v[118:121], v[64:79]
	v_cvt_pk_bf16_f32 v157, v10, v11
	v_cvt_pk_bf16_f32 v158, v84, v85
	v_cvt_pk_bf16_f32 v159, v12, v13
	v_cvt_pk_bf16_f32 v160, v14, v15
	v_cvt_pk_bf16_f32 v161, v8, v9
	v_add_u32_e32 v244, 0, v243
	v_add_u32_e32 v245, v89, v29
	v_mad_u64_u32 v[198:199], s[8:9], v88, s69, v[28:29]
	v_lshl_or_b32 v96, s44, 7, v96
	v_mov_b32_e32 v200, v32
	s_add_u32 s98, s40, 0x12380000
	s_addc_u32 s99, s41, 0
	s_add_u32 s100, s40, s30
	s_addc_u32 s101, s41, s31
	s_add_u32 s100, s100, 0x18380000
	s_addc_u32 s101, s101, 0
	v_lshl_add_u64 v[202:203], s[6:7], 0, v[30:31]
	s_mov_b64 s[42:43], 0
	v_mov_b32_e32 v162, 0
	v_mov_b32_e32 v163, 0
	v_mov_b32_e32 v164, 0
	v_mov_b32_e32 v165, 0
	v_mov_b32_e32 v166, 0
	v_mov_b32_e32 v167, 0
	v_mov_b32_e32 v168, 0
	v_mov_b32_e32 v169, 0
	s_mov_b32 s61, 0
	v_mov_b32_e32 v49, v48
	v_mov_b32_e32 v50, v48
	v_mov_b32_e32 v51, v48
	v_mov_b32_e32 v52, v48
	v_mov_b32_e32 v53, v48
	v_mov_b32_e32 v54, v48
	v_mov_b32_e32 v55, v48
	v_mov_b32_e32 v56, v48
	v_mov_b32_e32 v57, v48
	v_mov_b32_e32 v58, v48
	v_mov_b32_e32 v59, v48
	v_mov_b32_e32 v60, v48
	v_mov_b32_e32 v61, v48
	v_mov_b32_e32 v62, v48
	v_mov_b32_e32 v63, v48
	v_mov_b32_e32 v32, v48
	v_mov_b32_e32 v33, v48
	v_mov_b32_e32 v34, v48
	v_mov_b32_e32 v35, v48
	v_mov_b32_e32 v36, v48
	v_mov_b32_e32 v37, v48
	v_mov_b32_e32 v38, v48
	v_mov_b32_e32 v39, v48
	v_mov_b32_e32 v40, v48
	v_mov_b32_e32 v41, v48
	v_mov_b32_e32 v42, v48
	v_mov_b32_e32 v43, v48
	v_mov_b32_e32 v44, v48
	v_mov_b32_e32 v45, v48
	v_mov_b32_e32 v46, v48
	v_mov_b32_e32 v47, v48
	v_mov_b32_e32 v16, v48
	v_mov_b32_e32 v17, v48
	v_mov_b32_e32 v18, v48
	v_mov_b32_e32 v19, v48
	v_mov_b32_e32 v20, v48
	v_mov_b32_e32 v21, v48
	v_mov_b32_e32 v22, v48
	v_mov_b32_e32 v23, v48
	v_mov_b32_e32 v24, v48
	v_mov_b32_e32 v25, v48
	v_mov_b32_e32 v26, v48
	v_mov_b32_e32 v27, v48
	v_mov_b32_e32 v28, v48
	v_mov_b32_e32 v29, v48
	v_mov_b32_e32 v30, v48
	v_mov_b32_e32 v31, v48
	v_mov_b32_e32 v0, v48
	v_mov_b32_e32 v1, v48
	v_mov_b32_e32 v2, v48
	v_mov_b32_e32 v3, v48
	v_mov_b32_e32 v4, v48
	v_mov_b32_e32 v5, v48
	v_mov_b32_e32 v6, v48
	v_mov_b32_e32 v7, v48
	v_mov_b32_e32 v8, v48
	v_mov_b32_e32 v9, v48
	v_mov_b32_e32 v10, v48
	v_mov_b32_e32 v11, v48
	v_mov_b32_e32 v12, v48
	v_mov_b32_e32 v13, v48
	v_mov_b32_e32 v14, v48
	v_mov_b32_e32 v15, v48
	v_mov_b32_e32 v204, v48
	v_mov_b32_e32 v205, v48

.LBB0_925:
	s_cmpk_gt_u32 s61, 0xfb
	s_cbranch_scc1 .LBB0_927
	global_load_dwordx2 v[188:189], v[202:203], off offset:-4096
	global_load_dwordx4 v[142:145], v96, s[98:99]
	global_load_dwordx4 v[146:149], v200, s[100:101]
	s_add_u32 s98, s98, 0x20000
	s_addc_u32 s99, s99, 0
	s_add_u32 s100, s100, 0x20000
	s_addc_u32 s101, s101, 0

.LBB0_933:
	s_cmpk_gt_u32 s61, 0xfa
	s_cbranch_scc1 .LBB0_935
	global_load_dwordx2 v[190:191], v[202:203], off
	global_load_dwordx4 v[150:153], v96, s[98:99]
	global_load_dwordx4 v[138:141], v200, s[100:101]
	s_add_u32 s98, s98, 0x20000
	s_addc_u32 s99, s99, 0
	s_add_u32 s100, s100, 0x20000
	s_addc_u32 s101, s101, 0

; __global__ void __launch_bounds__(512) fwd_megakernel(Args a) {
;     extern __shared__ __attribute__((aligned(16))) unsigned char lds_raw[];
;     cg::grid_group grid = cg::this_grid();
	.amdhsa_kernel _Z14fwd_megakernel4Args
		.amdhsa_group_segment_fixed_size 0
		.amdhsa_private_segment_fixed_size 0
		.amdhsa_kernarg_size 432
		.amdhsa_user_sgpr_count 2
		.amdhsa_user_sgpr_dispatch_ptr 0
		.amdhsa_user_sgpr_queue_ptr 0
		.amdhsa_user_sgpr_kernarg_segment_ptr 1
		.amdhsa_user_sgpr_dispatch_id 0
		.amdhsa_user_sgpr_kernarg_preload_length 0
		.amdhsa_user_sgpr_kernarg_preload_offset 0
		.amdhsa_user_sgpr_private_segment_size 0
		.amdhsa_uses_dynamic_stack 0
		.amdhsa_enable_private_segment 0
		.amdhsa_system_sgpr_workgroup_id_x 1
		.amdhsa_system_sgpr_workgroup_id_y 0
		.amdhsa_system_sgpr_workgroup_id_z 0
		.amdhsa_system_sgpr_workgroup_info 0
		.amdhsa_system_vgpr_workitem_id 2
		.amdhsa_next_free_vgpr 256
		.amdhsa_next_free_sgpr 102
		.amdhsa_accum_offset 256
		.amdhsa_reserve_vcc 1
		.amdhsa_float_round_mode_32 0
		.amdhsa_float_round_mode_16_64 0
		.amdhsa_float_denorm_mode_32 3
		.amdhsa_float_denorm_mode_16_64 3
		.amdhsa_dx10_clamp 1
		.amdhsa_ieee_mode 1
		.amdhsa_fp16_overflow 0
		.amdhsa_tg_split 0
		.amdhsa_exception_fp_ieee_invalid_op 0
		.amdhsa_exception_fp_denorm_src 0
		.amdhsa_exception_fp_ieee_div_zero 0
		.amdhsa_exception_fp_ieee_overflow 0
		.amdhsa_exception_fp_ieee_underflow 0
		.amdhsa_exception_fp_ieee_inexact 0
		.amdhsa_exception_int_div_zero 0
	.end_amdhsa_kernel

; __global__ void __launch_bounds__(512) fwd_megakernel(Args a) {
;     extern __shared__ __attribute__((aligned(16))) unsigned char lds_raw[];
;     cg::grid_group grid = cg::this_grid();
amdhsa.kernels:
  - .agpr_count:     0
    .args:
      - .offset:         0
        .size:           176
        .value_kind:     by_value
      - .offset:         176
        .size:           4
        .value_kind:     hidden_block_count_x
      - .offset:         180
        .size:           4
        .value_kind:     hidden_block_count_y
      - .offset:         184
        .size:           4
        .value_kind:     hidden_block_count_z
      - .offset:         188
        .size:           2
        .value_kind:     hidden_group_size_x
      - .offset:         190
        .size:           2
        .value_kind:     hidden_group_size_y
      - .offset:         192
        .size:           2
        .value_kind:     hidden_group_size_z
      - .offset:         194
        .size:           2
        .value_kind:     hidden_remainder_x
      - .offset:         196
        .size:           2
        .value_kind:     hidden_remainder_y
      - .offset:         198
        .size:           2
        .value_kind:     hidden_remainder_z
      - .offset:         216
        .size:           8
        .value_kind:     hidden_global_offset_x
      - .offset:         224
        .size:           8
        .value_kind:     hidden_global_offset_y
      - .offset:         232
        .size:           8
        .value_kind:     hidden_global_offset_z
      - .offset:         240
        .size:           2
        .value_kind:     hidden_grid_dims
      - .offset:         264
        .size:           8
        .value_kind:     hidden_multigrid_sync_arg
      - .offset:         296
        .size:           4
        .value_kind:     hidden_dynamic_lds_size
    .group_segment_fixed_size: 0
    .kernarg_segment_align: 8
    .kernarg_segment_size: 432
    .language:       OpenCL C
    .language_version:
      - 2
      - 0
    .max_flat_workgroup_size: 512
    .name:           _Z14fwd_megakernel4Args
    .private_segment_fixed_size: 0
    .sgpr_count:     108
    .sgpr_spill_count: 72
    .symbol:         _Z14fwd_megakernel4Args.kd
    .uniform_work_group_size: 1
    .uses_dynamic_stack: false
    .vgpr_count:     256
    .vgpr_spill_count: 0
    .wavefront_size: 64
